# residual epilogue: stores issued one batch late with a 4th buffer so the write-through store acks sit further back in the in-order vmcnt window
# baseline (speedup 1.0000x reference)
; DI void outproj256(const Params& p, int layer, char* smem) {
;     ...
; #pragma unroll
;     for (int mi = 0; mi < 4; ++mi)
; #pragma unroll
;       for (int ni = 0; ni < 2; ++ni) {
;         const int col = tn * 256 + 64 * wn + 32 * ni + r;
;         const float gg = g1[col];
; #pragma unroll
;         for (int reg = 0; reg < 16; ++reg) {
;           const int row = 256 + tm * 256 + 128 * wm + 32 * mi + (reg & 3) + 8 * (reg >> 2) + 4 * h;
;           const float res = (layer == 0) ? __builtin_nontemporal_load(p.x + (size_t)(row - 256) * DM + col) : X[(size_t)row * DM + col];
;           X[(size_t)row * DM + col] = res + gg * acc[mi][ni][reg];
;         }
;       }
.LBB0_925:
	s_waitcnt vmcnt(0)
	v_and_b32_e32 v130, 0xdf, v0
	v_or_b32_e32 v130, s4, v130
	v_lshlrev_b32_e32 v130, 2, v130
	global_load_dword v137, v130, s[0:1]
	global_load_dword v138, v130, s[0:1] offset:128
	v_ashrrev_i32_e32 v131, 1, v0
	v_and_b32_e32 v131, 0xffffff80, v131
	v_add_u32_e32 v131, s22, v131
	v_lshrrev_b32_e32 v132, 3, v0
	v_and_or_b32 v131, v132, 4, v131
	v_lshl_add_u32 v133, v131, 13, v130
	v_add_u32_e32 v134, 0x2000, v133
	v_add_u32_e32 v135, 0x4000, v133
	v_add_u32_e32 v136, 0x6000, v133
	s_add_u32 s56, s68, 0xffe00000
	s_addc_u32 s57, s69, -1
	s_cmp_lg_u64 s[34:35], 0
	s_cselect_b32 s52, s90, s56
	s_cselect_b32 s53, s91, s57
	s_mov_b64 s[54:55], s[90:91]
	s_add_i32 s12, s12, 1
	s_add_u32 s56, s52, 0x0
	s_addc_u32 s57, s53, 0
	global_load_dword v193, v133, s[56:57]
	global_load_dword v194, v133, s[56:57] offset:128
	global_load_dword v195, v134, s[56:57]
	global_load_dword v196, v134, s[56:57] offset:128
	global_load_dword v197, v135, s[56:57]
	global_load_dword v198, v135, s[56:57] offset:128
	global_load_dword v199, v136, s[56:57]
	global_load_dword v200, v136, s[56:57] offset:128
	s_add_u32 s56, s52, 0x10000
	s_addc_u32 s57, s53, 0
	global_load_dword v201, v133, s[56:57]
	global_load_dword v202, v133, s[56:57] offset:128
	global_load_dword v203, v134, s[56:57]
	global_load_dword v204, v134, s[56:57] offset:128
	global_load_dword v205, v135, s[56:57]
	global_load_dword v206, v135, s[56:57] offset:128
	global_load_dword v207, v136, s[56:57]
	global_load_dword v208, v136, s[56:57] offset:128
	s_add_u32 s56, s52, 0x20000
	s_addc_u32 s57, s53, 0
	global_load_dword v209, v133, s[56:57]
	global_load_dword v210, v133, s[56:57] offset:128
	global_load_dword v211, v134, s[56:57]
	global_load_dword v212, v134, s[56:57] offset:128
	global_load_dword v213, v135, s[56:57]
	global_load_dword v214, v135, s[56:57] offset:128
	global_load_dword v215, v136, s[56:57]
	global_load_dword v216, v136, s[56:57] offset:128
	s_add_u32 s56, s52, 0x30000
	s_addc_u32 s57, s53, 0
	global_load_dword v217, v133, s[56:57]
	global_load_dword v218, v133, s[56:57] offset:128
	global_load_dword v219, v134, s[56:57]
	global_load_dword v220, v134, s[56:57] offset:128
	global_load_dword v221, v135, s[56:57]
	global_load_dword v222, v135, s[56:57] offset:128
	global_load_dword v223, v136, s[56:57]
	global_load_dword v224, v136, s[56:57] offset:128
	s_waitcnt vmcnt(16)
	v_fmac_f32_e32 v193, v114, v137
	v_fmac_f32_e32 v194, v98, v138
	v_fmac_f32_e32 v195, v115, v137
	v_fmac_f32_e32 v196, v99, v138
	v_fmac_f32_e32 v197, v116, v137
	v_fmac_f32_e32 v198, v100, v138
	v_fmac_f32_e32 v199, v117, v137
	v_fmac_f32_e32 v200, v101, v138
	v_fmac_f32_e32 v201, v118, v137
	v_fmac_f32_e32 v202, v102, v138
	v_fmac_f32_e32 v203, v119, v137
	v_fmac_f32_e32 v204, v103, v138
	v_fmac_f32_e32 v205, v120, v137
	v_fmac_f32_e32 v206, v104, v138
	v_fmac_f32_e32 v207, v121, v137
	v_fmac_f32_e32 v208, v105, v138
	s_add_u32 s56, s52, 0x40000
	s_addc_u32 s57, s53, 0
	global_load_dword v225, v133, s[56:57]
	global_load_dword v226, v133, s[56:57] offset:128
	global_load_dword v227, v134, s[56:57]
	global_load_dword v228, v134, s[56:57] offset:128
	global_load_dword v229, v135, s[56:57]
	global_load_dword v230, v135, s[56:57] offset:128
	global_load_dword v231, v136, s[56:57]
	global_load_dword v237, v136, s[56:57] offset:128
	s_add_u32 s56, s52, 0x50000
	s_addc_u32 s57, s53, 0
	global_load_dword v238, v133, s[56:57]
	global_load_dword v239, v133, s[56:57] offset:128
	global_load_dword v240, v134, s[56:57]
	global_load_dword v241, v134, s[56:57] offset:128
	global_load_dword v242, v135, s[56:57]
	global_load_dword v243, v135, s[56:57] offset:128
	global_load_dword v244, v136, s[56:57]
	global_load_dword v245, v136, s[56:57] offset:128
	s_waitcnt vmcnt(16)
	v_fmac_f32_e32 v209, v122, v137
	v_fmac_f32_e32 v210, v106, v138
	v_fmac_f32_e32 v211, v123, v137
	v_fmac_f32_e32 v212, v107, v138
	v_fmac_f32_e32 v213, v124, v137
	v_fmac_f32_e32 v214, v108, v138
	v_fmac_f32_e32 v215, v125, v137
	v_fmac_f32_e32 v216, v109, v138
	v_fmac_f32_e32 v217, v126, v137
	v_fmac_f32_e32 v218, v110, v138
	v_fmac_f32_e32 v219, v127, v137
	v_fmac_f32_e32 v220, v111, v138
	v_fmac_f32_e32 v221, v128, v137
	v_fmac_f32_e32 v222, v112, v138
	v_fmac_f32_e32 v223, v129, v137
	v_fmac_f32_e32 v224, v113, v138
	s_add_u32 s56, s52, 0x60000
	s_addc_u32 s57, s53, 0
	global_load_dword v140, v133, s[56:57]
	global_load_dword v141, v133, s[56:57] offset:128
	global_load_dword v142, v134, s[56:57]
	global_load_dword v143, v134, s[56:57] offset:128
	global_load_dword v144, v135, s[56:57]
	global_load_dword v145, v135, s[56:57] offset:128
	global_load_dword v146, v136, s[56:57]
	global_load_dword v147, v136, s[56:57] offset:128
	s_add_u32 s56, s52, 0x70000
	s_addc_u32 s57, s53, 0
	global_load_dword v148, v133, s[56:57]
	global_load_dword v149, v133, s[56:57] offset:128
	global_load_dword v150, v134, s[56:57]
	global_load_dword v151, v134, s[56:57] offset:128
	global_load_dword v152, v135, s[56:57]
	global_load_dword v153, v135, s[56:57] offset:128
	global_load_dword v154, v136, s[56:57]
	global_load_dword v155, v136, s[56:57] offset:128
	s_add_u32 s58, s54, 0x0
	s_addc_u32 s59, s55, 0
	global_store_dword v133, v193, s[58:59] sc0 sc1
	global_store_dword v133, v194, s[58:59] offset:128 sc0 sc1
	global_store_dword v134, v195, s[58:59] sc0 sc1
	global_store_dword v134, v196, s[58:59] offset:128 sc0 sc1
	global_store_dword v135, v197, s[58:59] sc0 sc1
	global_store_dword v135, v198, s[58:59] offset:128 sc0 sc1
	global_store_dword v136, v199, s[58:59] sc0 sc1
	global_store_dword v136, v200, s[58:59] offset:128 sc0 sc1
	s_add_u32 s58, s54, 0x10000
	s_addc_u32 s59, s55, 0
	global_store_dword v133, v201, s[58:59] sc0 sc1
	global_store_dword v133, v202, s[58:59] offset:128 sc0 sc1
	global_store_dword v134, v203, s[58:59] sc0 sc1
	global_store_dword v134, v204, s[58:59] offset:128 sc0 sc1
	global_store_dword v135, v205, s[58:59] sc0 sc1
	global_store_dword v135, v206, s[58:59] offset:128 sc0 sc1
	global_store_dword v136, v207, s[58:59] sc0 sc1
	global_store_dword v136, v208, s[58:59] offset:128 sc0 sc1
	s_waitcnt vmcnt(32)
; DI void outproj256(const Params& p, int layer, char* smem) {
;     ...
; #pragma unroll
;     for (int mi = 0; mi < 4; ++mi)
; #pragma unroll
;       for (int ni = 0; ni < 2; ++ni) {
;         const int col = tn * 256 + 64 * wn + 32 * ni + r;
;         const float gg = g1[col];
; #pragma unroll
;         for (int reg = 0; reg < 16; ++reg) {
;           const int row = 256 + tm * 256 + 128 * wm + 32 * mi + (reg & 3) + 8 * (reg >> 2) + 4 * h;
;           const float res = (layer == 0) ? __builtin_nontemporal_load(p.x + (size_t)(row - 256) * DM + col) : X[(size_t)row * DM + col];
;           X[(size_t)row * DM + col] = res + gg * acc[mi][ni][reg];
;         }
;       }
	v_fmac_f32_e32 v225, v82, v137
	v_fmac_f32_e32 v226, v66, v138
	v_fmac_f32_e32 v227, v83, v137
	v_fmac_f32_e32 v228, v67, v138
	v_fmac_f32_e32 v229, v84, v137
	v_fmac_f32_e32 v230, v68, v138
	v_fmac_f32_e32 v231, v85, v137
	v_fmac_f32_e32 v237, v69, v138
	v_fmac_f32_e32 v238, v86, v137
	v_fmac_f32_e32 v239, v70, v138
	v_fmac_f32_e32 v240, v87, v137
	v_fmac_f32_e32 v241, v71, v138
	v_fmac_f32_e32 v242, v88, v137
	v_fmac_f32_e32 v243, v72, v138
	v_fmac_f32_e32 v244, v89, v137
	v_fmac_f32_e32 v245, v73, v138
	s_add_u32 s56, s52, 0x80000
	s_addc_u32 s57, s53, 0
	global_load_dword v193, v133, s[56:57]
	global_load_dword v194, v133, s[56:57] offset:128
	global_load_dword v195, v134, s[56:57]
	global_load_dword v196, v134, s[56:57] offset:128
	global_load_dword v197, v135, s[56:57]
	global_load_dword v198, v135, s[56:57] offset:128
	global_load_dword v199, v136, s[56:57]
	global_load_dword v200, v136, s[56:57] offset:128
	s_add_u32 s56, s52, 0x90000
	s_addc_u32 s57, s53, 0
	global_load_dword v201, v133, s[56:57]
	global_load_dword v202, v133, s[56:57] offset:128
	global_load_dword v203, v134, s[56:57]
	global_load_dword v204, v134, s[56:57] offset:128
	global_load_dword v205, v135, s[56:57]
	global_load_dword v206, v135, s[56:57] offset:128
	global_load_dword v207, v136, s[56:57]
	global_load_dword v208, v136, s[56:57] offset:128
	s_add_u32 s58, s54, 0x20000
	s_addc_u32 s59, s55, 0
	global_store_dword v133, v209, s[58:59] sc0 sc1
	global_store_dword v133, v210, s[58:59] offset:128 sc0 sc1
	global_store_dword v134, v211, s[58:59] sc0 sc1
	global_store_dword v134, v212, s[58:59] offset:128 sc0 sc1
	global_store_dword v135, v213, s[58:59] sc0 sc1
	global_store_dword v135, v214, s[58:59] offset:128 sc0 sc1
	global_store_dword v136, v215, s[58:59] sc0 sc1
	global_store_dword v136, v216, s[58:59] offset:128 sc0 sc1
	s_add_u32 s58, s54, 0x30000
	s_addc_u32 s59, s55, 0
	global_store_dword v133, v217, s[58:59] sc0 sc1
	global_store_dword v133, v218, s[58:59] offset:128 sc0 sc1
	global_store_dword v134, v219, s[58:59] sc0 sc1
	global_store_dword v134, v220, s[58:59] offset:128 sc0 sc1
	global_store_dword v135, v221, s[58:59] sc0 sc1
	global_store_dword v135, v222, s[58:59] offset:128 sc0 sc1
	global_store_dword v136, v223, s[58:59] sc0 sc1
	global_store_dword v136, v224, s[58:59] offset:128 sc0 sc1
	s_waitcnt vmcnt(48)
	v_fmac_f32_e32 v140, v90, v137
	v_fmac_f32_e32 v141, v74, v138
	v_fmac_f32_e32 v142, v91, v137
	v_fmac_f32_e32 v143, v75, v138
	v_fmac_f32_e32 v144, v92, v137
	v_fmac_f32_e32 v145, v76, v138
	v_fmac_f32_e32 v146, v93, v137
	v_fmac_f32_e32 v147, v77, v138
	v_fmac_f32_e32 v148, v94, v137
	v_fmac_f32_e32 v149, v78, v138
	v_fmac_f32_e32 v150, v95, v137
	v_fmac_f32_e32 v151, v79, v138
	v_fmac_f32_e32 v152, v96, v137
	v_fmac_f32_e32 v153, v80, v138
	v_fmac_f32_e32 v154, v97, v137
	v_fmac_f32_e32 v155, v81, v138
	s_add_u32 s56, s52, 0xa0000
	s_addc_u32 s57, s53, 0
	global_load_dword v209, v133, s[56:57]
	global_load_dword v210, v133, s[56:57] offset:128
	global_load_dword v211, v134, s[56:57]
	global_load_dword v212, v134, s[56:57] offset:128
	global_load_dword v213, v135, s[56:57]
	global_load_dword v214, v135, s[56:57] offset:128
	global_load_dword v215, v136, s[56:57]
	global_load_dword v216, v136, s[56:57] offset:128
	s_add_u32 s56, s52, 0xb0000
	s_addc_u32 s57, s53, 0
	global_load_dword v217, v133, s[56:57]
	global_load_dword v218, v133, s[56:57] offset:128
	global_load_dword v219, v134, s[56:57]
	global_load_dword v220, v134, s[56:57] offset:128
	global_load_dword v221, v135, s[56:57]
	global_load_dword v222, v135, s[56:57] offset:128
	global_load_dword v223, v136, s[56:57]
	global_load_dword v224, v136, s[56:57] offset:128
	s_add_u32 s58, s54, 0x40000
	s_addc_u32 s59, s55, 0
	global_store_dword v133, v225, s[58:59] sc0 sc1
	global_store_dword v133, v226, s[58:59] offset:128 sc0 sc1
	global_store_dword v134, v227, s[58:59] sc0 sc1
	global_store_dword v134, v228, s[58:59] offset:128 sc0 sc1
	global_store_dword v135, v229, s[58:59] sc0 sc1
	global_store_dword v135, v230, s[58:59] offset:128 sc0 sc1
	global_store_dword v136, v231, s[58:59] sc0 sc1
	global_store_dword v136, v237, s[58:59] offset:128 sc0 sc1
	s_add_u32 s58, s54, 0x50000
	s_addc_u32 s59, s55, 0
	global_store_dword v133, v238, s[58:59] sc0 sc1
	global_store_dword v133, v239, s[58:59] offset:128 sc0 sc1
	global_store_dword v134, v240, s[58:59] sc0 sc1
	global_store_dword v134, v241, s[58:59] offset:128 sc0 sc1
	global_store_dword v135, v242, s[58:59] sc0 sc1
	global_store_dword v135, v243, s[58:59] offset:128 sc0 sc1
	global_store_dword v136, v244, s[58:59] sc0 sc1
	global_store_dword v136, v245, s[58:59] offset:128 sc0 sc1
	s_waitcnt vmcnt(48)
; DI void outproj256(const Params& p, int layer, char* smem) {
;     ...
; #pragma unroll
;     for (int mi = 0; mi < 4; ++mi)
; #pragma unroll
;       for (int ni = 0; ni < 2; ++ni) {
;         const int col = tn * 256 + 64 * wn + 32 * ni + r;
;         const float gg = g1[col];
; #pragma unroll
;         for (int reg = 0; reg < 16; ++reg) {
;           const int row = 256 + tm * 256 + 128 * wm + 32 * mi + (reg & 3) + 8 * (reg >> 2) + 4 * h;
;           const float res = (layer == 0) ? __builtin_nontemporal_load(p.x + (size_t)(row - 256) * DM + col) : X[(size_t)row * DM + col];
;           X[(size_t)row * DM + col] = res + gg * acc[mi][ni][reg];
;         }
;       }
	v_fmac_f32_e32 v193, v50, v137
	v_fmac_f32_e32 v194, v34, v138
	v_fmac_f32_e32 v195, v51, v137
	v_fmac_f32_e32 v196, v35, v138
	v_fmac_f32_e32 v197, v52, v137
	v_fmac_f32_e32 v198, v36, v138
	v_fmac_f32_e32 v199, v53, v137
	v_fmac_f32_e32 v200, v37, v138
	v_fmac_f32_e32 v201, v54, v137
	v_fmac_f32_e32 v202, v38, v138
	v_fmac_f32_e32 v203, v55, v137
	v_fmac_f32_e32 v204, v39, v138
	v_fmac_f32_e32 v205, v56, v137
	v_fmac_f32_e32 v206, v40, v138
	v_fmac_f32_e32 v207, v57, v137
	v_fmac_f32_e32 v208, v41, v138
	s_add_u32 s56, s52, 0xc0000
	s_addc_u32 s57, s53, 0
	global_load_dword v225, v133, s[56:57]
	global_load_dword v226, v133, s[56:57] offset:128
	global_load_dword v227, v134, s[56:57]
	global_load_dword v228, v134, s[56:57] offset:128
	global_load_dword v229, v135, s[56:57]
	global_load_dword v230, v135, s[56:57] offset:128
	global_load_dword v231, v136, s[56:57]
	global_load_dword v237, v136, s[56:57] offset:128
	s_add_u32 s56, s52, 0xd0000
	s_addc_u32 s57, s53, 0
	global_load_dword v238, v133, s[56:57]
	global_load_dword v239, v133, s[56:57] offset:128
	global_load_dword v240, v134, s[56:57]
	global_load_dword v241, v134, s[56:57] offset:128
	global_load_dword v242, v135, s[56:57]
	global_load_dword v243, v135, s[56:57] offset:128
	global_load_dword v244, v136, s[56:57]
	global_load_dword v245, v136, s[56:57] offset:128
	s_add_u32 s58, s54, 0x60000
	s_addc_u32 s59, s55, 0
	global_store_dword v133, v140, s[58:59] sc0 sc1
	global_store_dword v133, v141, s[58:59] offset:128 sc0 sc1
	global_store_dword v134, v142, s[58:59] sc0 sc1
	global_store_dword v134, v143, s[58:59] offset:128 sc0 sc1
	global_store_dword v135, v144, s[58:59] sc0 sc1
	global_store_dword v135, v145, s[58:59] offset:128 sc0 sc1
	global_store_dword v136, v146, s[58:59] sc0 sc1
	global_store_dword v136, v147, s[58:59] offset:128 sc0 sc1
	s_add_u32 s58, s54, 0x70000
	s_addc_u32 s59, s55, 0
	global_store_dword v133, v148, s[58:59] sc0 sc1
	global_store_dword v133, v149, s[58:59] offset:128 sc0 sc1
	global_store_dword v134, v150, s[58:59] sc0 sc1
	global_store_dword v134, v151, s[58:59] offset:128 sc0 sc1
	global_store_dword v135, v152, s[58:59] sc0 sc1
	global_store_dword v135, v153, s[58:59] offset:128 sc0 sc1
	global_store_dword v136, v154, s[58:59] sc0 sc1
	global_store_dword v136, v155, s[58:59] offset:128 sc0 sc1
	s_waitcnt vmcnt(48)
	v_fmac_f32_e32 v209, v58, v137
	v_fmac_f32_e32 v210, v42, v138
	v_fmac_f32_e32 v211, v59, v137
	v_fmac_f32_e32 v212, v43, v138
	v_fmac_f32_e32 v213, v60, v137
	v_fmac_f32_e32 v214, v44, v138
	v_fmac_f32_e32 v215, v61, v137
	v_fmac_f32_e32 v216, v45, v138
	v_fmac_f32_e32 v217, v62, v137
	v_fmac_f32_e32 v218, v46, v138
	v_fmac_f32_e32 v219, v63, v137
	v_fmac_f32_e32 v220, v47, v138
	v_fmac_f32_e32 v221, v64, v137
	v_fmac_f32_e32 v222, v48, v138
	v_fmac_f32_e32 v223, v65, v137
	v_fmac_f32_e32 v224, v49, v138
	s_add_u32 s56, s52, 0xe0000
	s_addc_u32 s57, s53, 0
	global_load_dword v140, v133, s[56:57]
	global_load_dword v141, v133, s[56:57] offset:128
	global_load_dword v142, v134, s[56:57]
	global_load_dword v143, v134, s[56:57] offset:128
	global_load_dword v144, v135, s[56:57]
	global_load_dword v145, v135, s[56:57] offset:128
	global_load_dword v146, v136, s[56:57]
	global_load_dword v147, v136, s[56:57] offset:128
	s_add_u32 s56, s52, 0xf0000
	s_addc_u32 s57, s53, 0
	global_load_dword v148, v133, s[56:57]
	global_load_dword v149, v133, s[56:57] offset:128
	global_load_dword v150, v134, s[56:57]
	global_load_dword v151, v134, s[56:57] offset:128
	global_load_dword v152, v135, s[56:57]
	global_load_dword v153, v135, s[56:57] offset:128
	global_load_dword v154, v136, s[56:57]
	global_load_dword v155, v136, s[56:57] offset:128
	s_add_u32 s58, s54, 0x80000
	s_addc_u32 s59, s55, 0
	global_store_dword v133, v193, s[58:59] sc0 sc1
	global_store_dword v133, v194, s[58:59] offset:128 sc0 sc1
	global_store_dword v134, v195, s[58:59] sc0 sc1
	global_store_dword v134, v196, s[58:59] offset:128 sc0 sc1
	global_store_dword v135, v197, s[58:59] sc0 sc1
	global_store_dword v135, v198, s[58:59] offset:128 sc0 sc1
	global_store_dword v136, v199, s[58:59] sc0 sc1
	global_store_dword v136, v200, s[58:59] offset:128 sc0 sc1
	s_add_u32 s58, s54, 0x90000
	s_addc_u32 s59, s55, 0
	global_store_dword v133, v201, s[58:59] sc0 sc1
	global_store_dword v133, v202, s[58:59] offset:128 sc0 sc1
	global_store_dword v134, v203, s[58:59] sc0 sc1
	global_store_dword v134, v204, s[58:59] offset:128 sc0 sc1
	global_store_dword v135, v205, s[58:59] sc0 sc1
	global_store_dword v135, v206, s[58:59] offset:128 sc0 sc1
	global_store_dword v136, v207, s[58:59] sc0 sc1
	global_store_dword v136, v208, s[58:59] offset:128 sc0 sc1
	s_waitcnt vmcnt(48)
; DI void outproj256(const Params& p, int layer, char* smem) {
;     ...
; #pragma unroll
;     for (int mi = 0; mi < 4; ++mi)
; #pragma unroll
;       for (int ni = 0; ni < 2; ++ni) {
;         const int col = tn * 256 + 64 * wn + 32 * ni + r;
;         const float gg = g1[col];
; #pragma unroll
;         for (int reg = 0; reg < 16; ++reg) {
;           const int row = 256 + tm * 256 + 128 * wm + 32 * mi + (reg & 3) + 8 * (reg >> 2) + 4 * h;
;           const float res = (layer == 0) ? __builtin_nontemporal_load(p.x + (size_t)(row - 256) * DM + col) : X[(size_t)row * DM + col];
;           X[(size_t)row * DM + col] = res + gg * acc[mi][ni][reg];
;         }
;       }
	v_fmac_f32_e32 v225, v18, v137
	v_fmac_f32_e32 v226, v2, v138
	v_fmac_f32_e32 v227, v19, v137
	v_fmac_f32_e32 v228, v3, v138
	v_fmac_f32_e32 v229, v20, v137
	v_fmac_f32_e32 v230, v4, v138
	v_fmac_f32_e32 v231, v21, v137
	v_fmac_f32_e32 v237, v5, v138
	v_fmac_f32_e32 v238, v22, v137
	v_fmac_f32_e32 v239, v6, v138
	v_fmac_f32_e32 v240, v23, v137
	v_fmac_f32_e32 v241, v7, v138
	v_fmac_f32_e32 v242, v24, v137
	v_fmac_f32_e32 v243, v8, v138
	v_fmac_f32_e32 v244, v25, v137
	v_fmac_f32_e32 v245, v9, v138
	s_add_u32 s58, s54, 0xa0000
	s_addc_u32 s59, s55, 0
	global_store_dword v133, v209, s[58:59] sc0 sc1
	global_store_dword v133, v210, s[58:59] offset:128 sc0 sc1
	global_store_dword v134, v211, s[58:59] sc0 sc1
	global_store_dword v134, v212, s[58:59] offset:128 sc0 sc1
	global_store_dword v135, v213, s[58:59] sc0 sc1
	global_store_dword v135, v214, s[58:59] offset:128 sc0 sc1
	global_store_dword v136, v215, s[58:59] sc0 sc1
	global_store_dword v136, v216, s[58:59] offset:128 sc0 sc1
	s_add_u32 s58, s54, 0xb0000
	s_addc_u32 s59, s55, 0
	global_store_dword v133, v217, s[58:59] sc0 sc1
	global_store_dword v133, v218, s[58:59] offset:128 sc0 sc1
	global_store_dword v134, v219, s[58:59] sc0 sc1
	global_store_dword v134, v220, s[58:59] offset:128 sc0 sc1
	global_store_dword v135, v221, s[58:59] sc0 sc1
	global_store_dword v135, v222, s[58:59] offset:128 sc0 sc1
	global_store_dword v136, v223, s[58:59] sc0 sc1
	global_store_dword v136, v224, s[58:59] offset:128 sc0 sc1
	s_waitcnt vmcnt(32)
	v_fmac_f32_e32 v140, v26, v137
	v_fmac_f32_e32 v141, v10, v138
	v_fmac_f32_e32 v142, v27, v137
	v_fmac_f32_e32 v143, v11, v138
	v_fmac_f32_e32 v144, v28, v137
	v_fmac_f32_e32 v145, v12, v138
	v_fmac_f32_e32 v146, v29, v137
	v_fmac_f32_e32 v147, v13, v138
	v_fmac_f32_e32 v148, v30, v137
	v_fmac_f32_e32 v149, v14, v138
	v_fmac_f32_e32 v150, v31, v137
	v_fmac_f32_e32 v151, v15, v138
	v_fmac_f32_e32 v152, v32, v137
	v_fmac_f32_e32 v153, v16, v138
	v_fmac_f32_e32 v154, v33, v137
	v_fmac_f32_e32 v155, v17, v138
	s_add_u32 s58, s54, 0xc0000
	s_addc_u32 s59, s55, 0
	global_store_dword v133, v225, s[58:59] sc0 sc1
	global_store_dword v133, v226, s[58:59] offset:128 sc0 sc1
	global_store_dword v134, v227, s[58:59] sc0 sc1
	global_store_dword v134, v228, s[58:59] offset:128 sc0 sc1
	global_store_dword v135, v229, s[58:59] sc0 sc1
	global_store_dword v135, v230, s[58:59] offset:128 sc0 sc1
	global_store_dword v136, v231, s[58:59] sc0 sc1
	global_store_dword v136, v237, s[58:59] offset:128 sc0 sc1
	s_add_u32 s58, s54, 0xd0000
	s_addc_u32 s59, s55, 0
	global_store_dword v133, v238, s[58:59] sc0 sc1
	global_store_dword v133, v239, s[58:59] offset:128 sc0 sc1
	global_store_dword v134, v240, s[58:59] sc0 sc1
	global_store_dword v134, v241, s[58:59] offset:128 sc0 sc1
	global_store_dword v135, v242, s[58:59] sc0 sc1
	global_store_dword v135, v243, s[58:59] offset:128 sc0 sc1
	global_store_dword v136, v244, s[58:59] sc0 sc1
	global_store_dword v136, v245, s[58:59] offset:128 sc0 sc1
	s_add_u32 s58, s54, 0xe0000
	s_addc_u32 s59, s55, 0
	global_store_dword v133, v140, s[58:59] sc0 sc1
	global_store_dword v133, v141, s[58:59] offset:128 sc0 sc1
	global_store_dword v134, v142, s[58:59] sc0 sc1
	global_store_dword v134, v143, s[58:59] offset:128 sc0 sc1
	global_store_dword v135, v144, s[58:59] sc0 sc1
	global_store_dword v135, v145, s[58:59] offset:128 sc0 sc1
	global_store_dword v136, v146, s[58:59] sc0 sc1
	global_store_dword v136, v147, s[58:59] offset:128 sc0 sc1
	s_add_u32 s58, s54, 0xf0000
	s_addc_u32 s59, s55, 0
	global_store_dword v133, v148, s[58:59] sc0 sc1
	global_store_dword v133, v149, s[58:59] offset:128 sc0 sc1
	global_store_dword v134, v150, s[58:59] sc0 sc1
	global_store_dword v134, v151, s[58:59] offset:128 sc0 sc1
	global_store_dword v135, v152, s[58:59] sc0 sc1
	global_store_dword v135, v153, s[58:59] offset:128 sc0 sc1
	global_store_dword v136, v154, s[58:59] sc0 sc1
	global_store_dword v136, v155, s[58:59] offset:128 sc0 sc1
	s_branch .LBB0_915

; DI void down256(const Params& p, int layer, char* smem) {
;     ...
; #pragma unroll
;     for (int mi = 0; mi < 4; ++mi)
; #pragma unroll
;       for (int ni = 0; ni < 2; ++ni) {
;         const int col = tn * 256 + 64 * wn + 32 * ni + r;
;         const float gg = g2[col];
; #pragma unroll
;         for (int reg = 0; reg < 16; ++reg) {
;           const int row = 256 + tm * 256 + 128 * wm + 32 * mi + (reg & 3) + 8 * (reg >> 2) + 4 * h;
;           X[(size_t)row * DM + col] += gg * acc[mi][ni][reg];
;         }
;       }
.LBB0_1646:
	s_waitcnt vmcnt(0)
	v_and_b32_e32 v130, 0xdf, v0
	v_or_b32_e32 v130, s12, v130
	v_lshlrev_b32_e32 v130, 2, v130
	global_load_dword v137, v130, s[0:1]
	global_load_dword v138, v130, s[0:1] offset:128
	v_ashrrev_i32_e32 v131, 1, v0
	v_and_b32_e32 v131, 0xffffff80, v131
	v_add_u32_e32 v131, s11, v131
	v_lshrrev_b32_e32 v132, 3, v0
	v_and_or_b32 v131, v132, 4, v131
	v_lshl_add_u32 v133, v131, 13, v130
	v_add_u32_e32 v134, 0x2000, v133
	v_add_u32_e32 v135, 0x4000, v133
	v_add_u32_e32 v136, 0x6000, v133
	s_mov_b64 s[52:53], s[90:91]
	s_mov_b64 s[54:55], s[90:91]
	s_add_i32 s10, s10, 1
	s_add_u32 s56, s52, 0x0
	s_addc_u32 s57, s53, 0
	global_load_dword v193, v133, s[56:57]
	global_load_dword v194, v133, s[56:57] offset:128
	global_load_dword v195, v134, s[56:57]
	global_load_dword v196, v134, s[56:57] offset:128
	global_load_dword v197, v135, s[56:57]
	global_load_dword v198, v135, s[56:57] offset:128
	global_load_dword v199, v136, s[56:57]
	global_load_dword v200, v136, s[56:57] offset:128
	s_add_u32 s56, s52, 0x10000
	s_addc_u32 s57, s53, 0
	global_load_dword v201, v133, s[56:57]
	global_load_dword v202, v133, s[56:57] offset:128
	global_load_dword v203, v134, s[56:57]
	global_load_dword v204, v134, s[56:57] offset:128
	global_load_dword v205, v135, s[56:57]
	global_load_dword v206, v135, s[56:57] offset:128
	global_load_dword v207, v136, s[56:57]
	global_load_dword v208, v136, s[56:57] offset:128
	s_add_u32 s56, s52, 0x20000
	s_addc_u32 s57, s53, 0
	global_load_dword v209, v133, s[56:57]
	global_load_dword v210, v133, s[56:57] offset:128
	global_load_dword v211, v134, s[56:57]
	global_load_dword v212, v134, s[56:57] offset:128
	global_load_dword v213, v135, s[56:57]
	global_load_dword v214, v135, s[56:57] offset:128
	global_load_dword v215, v136, s[56:57]
	global_load_dword v216, v136, s[56:57] offset:128
	s_add_u32 s56, s52, 0x30000
	s_addc_u32 s57, s53, 0
	global_load_dword v217, v133, s[56:57]
	global_load_dword v218, v133, s[56:57] offset:128
	global_load_dword v219, v134, s[56:57]
	global_load_dword v220, v134, s[56:57] offset:128
	global_load_dword v221, v135, s[56:57]
	global_load_dword v222, v135, s[56:57] offset:128
	global_load_dword v223, v136, s[56:57]
	global_load_dword v224, v136, s[56:57] offset:128
	s_waitcnt vmcnt(16)
	v_fmac_f32_e32 v193, v114, v137
	v_fmac_f32_e32 v194, v98, v138
	v_fmac_f32_e32 v195, v115, v137
	v_fmac_f32_e32 v196, v99, v138
	v_fmac_f32_e32 v197, v116, v137
	v_fmac_f32_e32 v198, v100, v138
	v_fmac_f32_e32 v199, v117, v137
	v_fmac_f32_e32 v200, v101, v138
	v_fmac_f32_e32 v201, v118, v137
	v_fmac_f32_e32 v202, v102, v138
	v_fmac_f32_e32 v203, v119, v137
	v_fmac_f32_e32 v204, v103, v138
	v_fmac_f32_e32 v205, v120, v137
	v_fmac_f32_e32 v206, v104, v138
	v_fmac_f32_e32 v207, v121, v137
	v_fmac_f32_e32 v208, v105, v138
	s_add_u32 s56, s52, 0x40000
	s_addc_u32 s57, s53, 0
	global_load_dword v225, v133, s[56:57]
	global_load_dword v226, v133, s[56:57] offset:128
	global_load_dword v227, v134, s[56:57]
	global_load_dword v228, v134, s[56:57] offset:128
	global_load_dword v229, v135, s[56:57]
	global_load_dword v230, v135, s[56:57] offset:128
	global_load_dword v231, v136, s[56:57]
	global_load_dword v237, v136, s[56:57] offset:128
	s_add_u32 s56, s52, 0x50000
	s_addc_u32 s57, s53, 0
	global_load_dword v238, v133, s[56:57]
	global_load_dword v239, v133, s[56:57] offset:128
	global_load_dword v240, v134, s[56:57]
	global_load_dword v241, v134, s[56:57] offset:128
	global_load_dword v242, v135, s[56:57]
	global_load_dword v243, v135, s[56:57] offset:128
	global_load_dword v244, v136, s[56:57]
	global_load_dword v245, v136, s[56:57] offset:128
	s_waitcnt vmcnt(16)
	v_fmac_f32_e32 v209, v122, v137
	v_fmac_f32_e32 v210, v106, v138
	v_fmac_f32_e32 v211, v123, v137
	v_fmac_f32_e32 v212, v107, v138
	v_fmac_f32_e32 v213, v124, v137
	v_fmac_f32_e32 v214, v108, v138
	v_fmac_f32_e32 v215, v125, v137
	v_fmac_f32_e32 v216, v109, v138
	v_fmac_f32_e32 v217, v126, v137
	v_fmac_f32_e32 v218, v110, v138
	v_fmac_f32_e32 v219, v127, v137
	v_fmac_f32_e32 v220, v111, v138
	v_fmac_f32_e32 v221, v128, v137
	v_fmac_f32_e32 v222, v112, v138
	v_fmac_f32_e32 v223, v129, v137
	v_fmac_f32_e32 v224, v113, v138
	s_add_u32 s56, s52, 0x60000
	s_addc_u32 s57, s53, 0
	global_load_dword v140, v133, s[56:57]
	global_load_dword v141, v133, s[56:57] offset:128
	global_load_dword v142, v134, s[56:57]
	global_load_dword v143, v134, s[56:57] offset:128
	global_load_dword v144, v135, s[56:57]
	global_load_dword v145, v135, s[56:57] offset:128
	global_load_dword v146, v136, s[56:57]
	global_load_dword v147, v136, s[56:57] offset:128
	s_add_u32 s56, s52, 0x70000
	s_addc_u32 s57, s53, 0
	global_load_dword v148, v133, s[56:57]
	global_load_dword v149, v133, s[56:57] offset:128
	global_load_dword v150, v134, s[56:57]
	global_load_dword v151, v134, s[56:57] offset:128
	global_load_dword v152, v135, s[56:57]
	global_load_dword v153, v135, s[56:57] offset:128
	global_load_dword v154, v136, s[56:57]
	global_load_dword v155, v136, s[56:57] offset:128
	s_add_u32 s58, s54, 0x0
	s_addc_u32 s59, s55, 0
	global_store_dword v133, v193, s[58:59] sc0 sc1
	global_store_dword v133, v194, s[58:59] offset:128 sc0 sc1
	global_store_dword v134, v195, s[58:59] sc0 sc1
	global_store_dword v134, v196, s[58:59] offset:128 sc0 sc1
	global_store_dword v135, v197, s[58:59] sc0 sc1
	global_store_dword v135, v198, s[58:59] offset:128 sc0 sc1
	global_store_dword v136, v199, s[58:59] sc0 sc1
	global_store_dword v136, v200, s[58:59] offset:128 sc0 sc1
	s_add_u32 s58, s54, 0x10000
	s_addc_u32 s59, s55, 0
	global_store_dword v133, v201, s[58:59] sc0 sc1
	global_store_dword v133, v202, s[58:59] offset:128 sc0 sc1
	global_store_dword v134, v203, s[58:59] sc0 sc1
	global_store_dword v134, v204, s[58:59] offset:128 sc0 sc1
	global_store_dword v135, v205, s[58:59] sc0 sc1
	global_store_dword v135, v206, s[58:59] offset:128 sc0 sc1
	global_store_dword v136, v207, s[58:59] sc0 sc1
	global_store_dword v136, v208, s[58:59] offset:128 sc0 sc1
	s_waitcnt vmcnt(32)
; DI void down256(const Params& p, int layer, char* smem) {
;     ...
; #pragma unroll
;     for (int mi = 0; mi < 4; ++mi)
; #pragma unroll
;       for (int ni = 0; ni < 2; ++ni) {
;         const int col = tn * 256 + 64 * wn + 32 * ni + r;
;         const float gg = g2[col];
; #pragma unroll
;         for (int reg = 0; reg < 16; ++reg) {
;           const int row = 256 + tm * 256 + 128 * wm + 32 * mi + (reg & 3) + 8 * (reg >> 2) + 4 * h;
;           X[(size_t)row * DM + col] += gg * acc[mi][ni][reg];
;         }
;       }
	v_fmac_f32_e32 v225, v82, v137
	v_fmac_f32_e32 v226, v66, v138
	v_fmac_f32_e32 v227, v83, v137
	v_fmac_f32_e32 v228, v67, v138
	v_fmac_f32_e32 v229, v84, v137
	v_fmac_f32_e32 v230, v68, v138
	v_fmac_f32_e32 v231, v85, v137
	v_fmac_f32_e32 v237, v69, v138
	v_fmac_f32_e32 v238, v86, v137
	v_fmac_f32_e32 v239, v70, v138
	v_fmac_f32_e32 v240, v87, v137
	v_fmac_f32_e32 v241, v71, v138
	v_fmac_f32_e32 v242, v88, v137
	v_fmac_f32_e32 v243, v72, v138
	v_fmac_f32_e32 v244, v89, v137
	v_fmac_f32_e32 v245, v73, v138
	s_add_u32 s56, s52, 0x80000
	s_addc_u32 s57, s53, 0
	global_load_dword v193, v133, s[56:57]
	global_load_dword v194, v133, s[56:57] offset:128
	global_load_dword v195, v134, s[56:57]
	global_load_dword v196, v134, s[56:57] offset:128
	global_load_dword v197, v135, s[56:57]
	global_load_dword v198, v135, s[56:57] offset:128
	global_load_dword v199, v136, s[56:57]
	global_load_dword v200, v136, s[56:57] offset:128
	s_add_u32 s56, s52, 0x90000
	s_addc_u32 s57, s53, 0
	global_load_dword v201, v133, s[56:57]
	global_load_dword v202, v133, s[56:57] offset:128
	global_load_dword v203, v134, s[56:57]
	global_load_dword v204, v134, s[56:57] offset:128
	global_load_dword v205, v135, s[56:57]
	global_load_dword v206, v135, s[56:57] offset:128
	global_load_dword v207, v136, s[56:57]
	global_load_dword v208, v136, s[56:57] offset:128
	s_add_u32 s58, s54, 0x20000
	s_addc_u32 s59, s55, 0
	global_store_dword v133, v209, s[58:59] sc0 sc1
	global_store_dword v133, v210, s[58:59] offset:128 sc0 sc1
	global_store_dword v134, v211, s[58:59] sc0 sc1
	global_store_dword v134, v212, s[58:59] offset:128 sc0 sc1
	global_store_dword v135, v213, s[58:59] sc0 sc1
	global_store_dword v135, v214, s[58:59] offset:128 sc0 sc1
	global_store_dword v136, v215, s[58:59] sc0 sc1
	global_store_dword v136, v216, s[58:59] offset:128 sc0 sc1
	s_add_u32 s58, s54, 0x30000
	s_addc_u32 s59, s55, 0
	global_store_dword v133, v217, s[58:59] sc0 sc1
	global_store_dword v133, v218, s[58:59] offset:128 sc0 sc1
	global_store_dword v134, v219, s[58:59] sc0 sc1
	global_store_dword v134, v220, s[58:59] offset:128 sc0 sc1
	global_store_dword v135, v221, s[58:59] sc0 sc1
	global_store_dword v135, v222, s[58:59] offset:128 sc0 sc1
	global_store_dword v136, v223, s[58:59] sc0 sc1
	global_store_dword v136, v224, s[58:59] offset:128 sc0 sc1
	s_waitcnt vmcnt(48)
	v_fmac_f32_e32 v140, v90, v137
	v_fmac_f32_e32 v141, v74, v138
	v_fmac_f32_e32 v142, v91, v137
	v_fmac_f32_e32 v143, v75, v138
	v_fmac_f32_e32 v144, v92, v137
	v_fmac_f32_e32 v145, v76, v138
	v_fmac_f32_e32 v146, v93, v137
	v_fmac_f32_e32 v147, v77, v138
	v_fmac_f32_e32 v148, v94, v137
	v_fmac_f32_e32 v149, v78, v138
	v_fmac_f32_e32 v150, v95, v137
	v_fmac_f32_e32 v151, v79, v138
	v_fmac_f32_e32 v152, v96, v137
	v_fmac_f32_e32 v153, v80, v138
	v_fmac_f32_e32 v154, v97, v137
	v_fmac_f32_e32 v155, v81, v138
	s_add_u32 s56, s52, 0xa0000
	s_addc_u32 s57, s53, 0
	global_load_dword v209, v133, s[56:57]
	global_load_dword v210, v133, s[56:57] offset:128
	global_load_dword v211, v134, s[56:57]
	global_load_dword v212, v134, s[56:57] offset:128
	global_load_dword v213, v135, s[56:57]
	global_load_dword v214, v135, s[56:57] offset:128
	global_load_dword v215, v136, s[56:57]
	global_load_dword v216, v136, s[56:57] offset:128
	s_add_u32 s56, s52, 0xb0000
	s_addc_u32 s57, s53, 0
	global_load_dword v217, v133, s[56:57]
	global_load_dword v218, v133, s[56:57] offset:128
	global_load_dword v219, v134, s[56:57]
	global_load_dword v220, v134, s[56:57] offset:128
	global_load_dword v221, v135, s[56:57]
	global_load_dword v222, v135, s[56:57] offset:128
	global_load_dword v223, v136, s[56:57]
	global_load_dword v224, v136, s[56:57] offset:128
	s_add_u32 s58, s54, 0x40000
	s_addc_u32 s59, s55, 0
	global_store_dword v133, v225, s[58:59] sc0 sc1
	global_store_dword v133, v226, s[58:59] offset:128 sc0 sc1
	global_store_dword v134, v227, s[58:59] sc0 sc1
	global_store_dword v134, v228, s[58:59] offset:128 sc0 sc1
	global_store_dword v135, v229, s[58:59] sc0 sc1
	global_store_dword v135, v230, s[58:59] offset:128 sc0 sc1
	global_store_dword v136, v231, s[58:59] sc0 sc1
	global_store_dword v136, v237, s[58:59] offset:128 sc0 sc1
	s_add_u32 s58, s54, 0x50000
	s_addc_u32 s59, s55, 0
	global_store_dword v133, v238, s[58:59] sc0 sc1
	global_store_dword v133, v239, s[58:59] offset:128 sc0 sc1
	global_store_dword v134, v240, s[58:59] sc0 sc1
	global_store_dword v134, v241, s[58:59] offset:128 sc0 sc1
	global_store_dword v135, v242, s[58:59] sc0 sc1
	global_store_dword v135, v243, s[58:59] offset:128 sc0 sc1
	global_store_dword v136, v244, s[58:59] sc0 sc1
	global_store_dword v136, v245, s[58:59] offset:128 sc0 sc1
	s_waitcnt vmcnt(48)
; DI void down256(const Params& p, int layer, char* smem) {
;     ...
; #pragma unroll
;     for (int mi = 0; mi < 4; ++mi)
; #pragma unroll
;       for (int ni = 0; ni < 2; ++ni) {
;         const int col = tn * 256 + 64 * wn + 32 * ni + r;
;         const float gg = g2[col];
; #pragma unroll
;         for (int reg = 0; reg < 16; ++reg) {
;           const int row = 256 + tm * 256 + 128 * wm + 32 * mi + (reg & 3) + 8 * (reg >> 2) + 4 * h;
;           X[(size_t)row * DM + col] += gg * acc[mi][ni][reg];
;         }
;       }
	v_fmac_f32_e32 v193, v50, v137
	v_fmac_f32_e32 v194, v34, v138
	v_fmac_f32_e32 v195, v51, v137
	v_fmac_f32_e32 v196, v35, v138
	v_fmac_f32_e32 v197, v52, v137
	v_fmac_f32_e32 v198, v36, v138
	v_fmac_f32_e32 v199, v53, v137
	v_fmac_f32_e32 v200, v37, v138
	v_fmac_f32_e32 v201, v54, v137
	v_fmac_f32_e32 v202, v38, v138
	v_fmac_f32_e32 v203, v55, v137
	v_fmac_f32_e32 v204, v39, v138
	v_fmac_f32_e32 v205, v56, v137
	v_fmac_f32_e32 v206, v40, v138
	v_fmac_f32_e32 v207, v57, v137
	v_fmac_f32_e32 v208, v41, v138
	s_add_u32 s56, s52, 0xc0000
	s_addc_u32 s57, s53, 0
	global_load_dword v225, v133, s[56:57]
	global_load_dword v226, v133, s[56:57] offset:128
	global_load_dword v227, v134, s[56:57]
	global_load_dword v228, v134, s[56:57] offset:128
	global_load_dword v229, v135, s[56:57]
	global_load_dword v230, v135, s[56:57] offset:128
	global_load_dword v231, v136, s[56:57]
	global_load_dword v237, v136, s[56:57] offset:128
	s_add_u32 s56, s52, 0xd0000
	s_addc_u32 s57, s53, 0
	global_load_dword v238, v133, s[56:57]
	global_load_dword v239, v133, s[56:57] offset:128
	global_load_dword v240, v134, s[56:57]
	global_load_dword v241, v134, s[56:57] offset:128
	global_load_dword v242, v135, s[56:57]
	global_load_dword v243, v135, s[56:57] offset:128
	global_load_dword v244, v136, s[56:57]
	global_load_dword v245, v136, s[56:57] offset:128
	s_add_u32 s58, s54, 0x60000
	s_addc_u32 s59, s55, 0
	global_store_dword v133, v140, s[58:59] sc0 sc1
	global_store_dword v133, v141, s[58:59] offset:128 sc0 sc1
	global_store_dword v134, v142, s[58:59] sc0 sc1
	global_store_dword v134, v143, s[58:59] offset:128 sc0 sc1
	global_store_dword v135, v144, s[58:59] sc0 sc1
	global_store_dword v135, v145, s[58:59] offset:128 sc0 sc1
	global_store_dword v136, v146, s[58:59] sc0 sc1
	global_store_dword v136, v147, s[58:59] offset:128 sc0 sc1
	s_add_u32 s58, s54, 0x70000
	s_addc_u32 s59, s55, 0
	global_store_dword v133, v148, s[58:59] sc0 sc1
	global_store_dword v133, v149, s[58:59] offset:128 sc0 sc1
	global_store_dword v134, v150, s[58:59] sc0 sc1
	global_store_dword v134, v151, s[58:59] offset:128 sc0 sc1
	global_store_dword v135, v152, s[58:59] sc0 sc1
	global_store_dword v135, v153, s[58:59] offset:128 sc0 sc1
	global_store_dword v136, v154, s[58:59] sc0 sc1
	global_store_dword v136, v155, s[58:59] offset:128 sc0 sc1
	s_waitcnt vmcnt(48)
	v_fmac_f32_e32 v209, v58, v137
	v_fmac_f32_e32 v210, v42, v138
	v_fmac_f32_e32 v211, v59, v137
	v_fmac_f32_e32 v212, v43, v138
	v_fmac_f32_e32 v213, v60, v137
	v_fmac_f32_e32 v214, v44, v138
	v_fmac_f32_e32 v215, v61, v137
	v_fmac_f32_e32 v216, v45, v138
	v_fmac_f32_e32 v217, v62, v137
	v_fmac_f32_e32 v218, v46, v138
	v_fmac_f32_e32 v219, v63, v137
	v_fmac_f32_e32 v220, v47, v138
	v_fmac_f32_e32 v221, v64, v137
	v_fmac_f32_e32 v222, v48, v138
	v_fmac_f32_e32 v223, v65, v137
	v_fmac_f32_e32 v224, v49, v138
	s_add_u32 s56, s52, 0xe0000
	s_addc_u32 s57, s53, 0
	global_load_dword v140, v133, s[56:57]
	global_load_dword v141, v133, s[56:57] offset:128
	global_load_dword v142, v134, s[56:57]
	global_load_dword v143, v134, s[56:57] offset:128
	global_load_dword v144, v135, s[56:57]
	global_load_dword v145, v135, s[56:57] offset:128
	global_load_dword v146, v136, s[56:57]
	global_load_dword v147, v136, s[56:57] offset:128
	s_add_u32 s56, s52, 0xf0000
	s_addc_u32 s57, s53, 0
	global_load_dword v148, v133, s[56:57]
	global_load_dword v149, v133, s[56:57] offset:128
	global_load_dword v150, v134, s[56:57]
	global_load_dword v151, v134, s[56:57] offset:128
	global_load_dword v152, v135, s[56:57]
	global_load_dword v153, v135, s[56:57] offset:128
	global_load_dword v154, v136, s[56:57]
	global_load_dword v155, v136, s[56:57] offset:128
	s_add_u32 s58, s54, 0x80000
	s_addc_u32 s59, s55, 0
	global_store_dword v133, v193, s[58:59] sc0 sc1
	global_store_dword v133, v194, s[58:59] offset:128 sc0 sc1
	global_store_dword v134, v195, s[58:59] sc0 sc1
	global_store_dword v134, v196, s[58:59] offset:128 sc0 sc1
	global_store_dword v135, v197, s[58:59] sc0 sc1
	global_store_dword v135, v198, s[58:59] offset:128 sc0 sc1
	global_store_dword v136, v199, s[58:59] sc0 sc1
	global_store_dword v136, v200, s[58:59] offset:128 sc0 sc1
	s_add_u32 s58, s54, 0x90000
	s_addc_u32 s59, s55, 0
	global_store_dword v133, v201, s[58:59] sc0 sc1
	global_store_dword v133, v202, s[58:59] offset:128 sc0 sc1
	global_store_dword v134, v203, s[58:59] sc0 sc1
	global_store_dword v134, v204, s[58:59] offset:128 sc0 sc1
	global_store_dword v135, v205, s[58:59] sc0 sc1
	global_store_dword v135, v206, s[58:59] offset:128 sc0 sc1
	global_store_dword v136, v207, s[58:59] sc0 sc1
	global_store_dword v136, v208, s[58:59] offset:128 sc0 sc1
	s_waitcnt vmcnt(48)
; DI void down256(const Params& p, int layer, char* smem) {
;     ...
; #pragma unroll
;     for (int mi = 0; mi < 4; ++mi)
; #pragma unroll
;       for (int ni = 0; ni < 2; ++ni) {
;         const int col = tn * 256 + 64 * wn + 32 * ni + r;
;         const float gg = g2[col];
; #pragma unroll
;         for (int reg = 0; reg < 16; ++reg) {
;           const int row = 256 + tm * 256 + 128 * wm + 32 * mi + (reg & 3) + 8 * (reg >> 2) + 4 * h;
;           X[(size_t)row * DM + col] += gg * acc[mi][ni][reg];
;         }
;       }
	v_fmac_f32_e32 v225, v18, v137
	v_fmac_f32_e32 v226, v2, v138
	v_fmac_f32_e32 v227, v19, v137
	v_fmac_f32_e32 v228, v3, v138
	v_fmac_f32_e32 v229, v20, v137
	v_fmac_f32_e32 v230, v4, v138
	v_fmac_f32_e32 v231, v21, v137
	v_fmac_f32_e32 v237, v5, v138
	v_fmac_f32_e32 v238, v22, v137
	v_fmac_f32_e32 v239, v6, v138
	v_fmac_f32_e32 v240, v23, v137
	v_fmac_f32_e32 v241, v7, v138
	v_fmac_f32_e32 v242, v24, v137
	v_fmac_f32_e32 v243, v8, v138
	v_fmac_f32_e32 v244, v25, v137
	v_fmac_f32_e32 v245, v9, v138
	s_add_u32 s58, s54, 0xa0000
	s_addc_u32 s59, s55, 0
	global_store_dword v133, v209, s[58:59] sc0 sc1
	global_store_dword v133, v210, s[58:59] offset:128 sc0 sc1
	global_store_dword v134, v211, s[58:59] sc0 sc1
	global_store_dword v134, v212, s[58:59] offset:128 sc0 sc1
	global_store_dword v135, v213, s[58:59] sc0 sc1
	global_store_dword v135, v214, s[58:59] offset:128 sc0 sc1
	global_store_dword v136, v215, s[58:59] sc0 sc1
	global_store_dword v136, v216, s[58:59] offset:128 sc0 sc1
	s_add_u32 s58, s54, 0xb0000
	s_addc_u32 s59, s55, 0
	global_store_dword v133, v217, s[58:59] sc0 sc1
	global_store_dword v133, v218, s[58:59] offset:128 sc0 sc1
	global_store_dword v134, v219, s[58:59] sc0 sc1
	global_store_dword v134, v220, s[58:59] offset:128 sc0 sc1
	global_store_dword v135, v221, s[58:59] sc0 sc1
	global_store_dword v135, v222, s[58:59] offset:128 sc0 sc1
	global_store_dword v136, v223, s[58:59] sc0 sc1
	global_store_dword v136, v224, s[58:59] offset:128 sc0 sc1
	s_waitcnt vmcnt(32)
	v_fmac_f32_e32 v140, v26, v137
	v_fmac_f32_e32 v141, v10, v138
	v_fmac_f32_e32 v142, v27, v137
	v_fmac_f32_e32 v143, v11, v138
	v_fmac_f32_e32 v144, v28, v137
	v_fmac_f32_e32 v145, v12, v138
	v_fmac_f32_e32 v146, v29, v137
	v_fmac_f32_e32 v147, v13, v138
	v_fmac_f32_e32 v148, v30, v137
	v_fmac_f32_e32 v149, v14, v138
	v_fmac_f32_e32 v150, v31, v137
	v_fmac_f32_e32 v151, v15, v138
	v_fmac_f32_e32 v152, v32, v137
	v_fmac_f32_e32 v153, v16, v138
	v_fmac_f32_e32 v154, v33, v137
	v_fmac_f32_e32 v155, v17, v138
	s_add_u32 s58, s54, 0xc0000
	s_addc_u32 s59, s55, 0
	global_store_dword v133, v225, s[58:59] sc0 sc1
	global_store_dword v133, v226, s[58:59] offset:128 sc0 sc1
	global_store_dword v134, v227, s[58:59] sc0 sc1
	global_store_dword v134, v228, s[58:59] offset:128 sc0 sc1
	global_store_dword v135, v229, s[58:59] sc0 sc1
	global_store_dword v135, v230, s[58:59] offset:128 sc0 sc1
	global_store_dword v136, v231, s[58:59] sc0 sc1
	global_store_dword v136, v237, s[58:59] offset:128 sc0 sc1
	s_add_u32 s58, s54, 0xd0000
	s_addc_u32 s59, s55, 0
	global_store_dword v133, v238, s[58:59] sc0 sc1
	global_store_dword v133, v239, s[58:59] offset:128 sc0 sc1
	global_store_dword v134, v240, s[58:59] sc0 sc1
	global_store_dword v134, v241, s[58:59] offset:128 sc0 sc1
	global_store_dword v135, v242, s[58:59] sc0 sc1
	global_store_dword v135, v243, s[58:59] offset:128 sc0 sc1
	global_store_dword v136, v244, s[58:59] sc0 sc1
	global_store_dword v136, v245, s[58:59] offset:128 sc0 sc1
	s_add_u32 s58, s54, 0xe0000
	s_addc_u32 s59, s55, 0
	global_store_dword v133, v140, s[58:59] sc0 sc1
	global_store_dword v133, v141, s[58:59] offset:128 sc0 sc1
	global_store_dword v134, v142, s[58:59] sc0 sc1
	global_store_dword v134, v143, s[58:59] offset:128 sc0 sc1
	global_store_dword v135, v144, s[58:59] sc0 sc1
	global_store_dword v135, v145, s[58:59] offset:128 sc0 sc1
	global_store_dword v136, v146, s[58:59] sc0 sc1
	global_store_dword v136, v147, s[58:59] offset:128 sc0 sc1
	s_add_u32 s58, s54, 0xf0000
	s_addc_u32 s59, s55, 0
	global_store_dword v133, v148, s[58:59] sc0 sc1
	global_store_dword v133, v149, s[58:59] offset:128 sc0 sc1
	global_store_dword v134, v150, s[58:59] sc0 sc1
	global_store_dword v134, v151, s[58:59] offset:128 sc0 sc1
	global_store_dword v135, v152, s[58:59] sc0 sc1
	global_store_dword v135, v153, s[58:59] offset:128 sc0 sc1
	global_store_dword v136, v154, s[58:59] sc0 sc1
	global_store_dword v136, v155, s[58:59] offset:128 sc0 sc1
	s_branch .LBB0_1637
